# weight-copy publication atomic moved after the phase-3/4 glue's closing barrier (no extra barrier, atomic no longer ahead of the poll)
# baseline (speedup 1.0000x reference)
; #define GSYNC() do { xcd_barrier(xbar); xcd_barrier(xbar); } while (0)
; #define GSYNC() xcd_barrier(xbar)
; #define REP(p) for (int rep_ = 0; rep_ < (((PROBE_MASK >> (p)) & 1) ? 2 : 1); ++rep_)
; __device__ __forceinline__ void hgrn_scan_phase(const float* __restrict__ Lst, const float* __restrict__ Dtot, float* __restrict__ Sst, int G) {
;     ...
;     for (int e = blockIdx.x * NTHR + tid; e < 8 * 16384; e += G * NTHR) {
;         const int bh = e >> 14, kv = e & 16383, kk = kv >> 7;
; __global__ void __launch_bounds__(NTHR, 2) fwd_megakernel(Args args) {
;     ...
;     weight_copy_items(args, lds, 16 * 96 + 32, 16 * 96 + 32 + 16 * 32 + 16 * 129 + 16 * 32, G);
;     GSYNC(); }
;     REP(4) { hgrn_scan_phase((const float*)(ws + WS_LST), (const float*)(ws + WS_DTOT), (float*)(ws + WS_SST), G);
.Lp4_polled:
	s_mov_b64 exec, s[100:101]
	s_waitcnt lgkmcnt(0)
	v_mov_b32_e32 v0, v216
	s_barrier
	s_and_saveexec_b64 s[100:101], s[92:93]
	s_cbranch_execz .Lp4_c2done
	s_and_b32 s98, s91, 15
	s_lshl_b32 s98, s98, 6
	s_add_i32 s98, s98, 0x2000
	v_mov_b32_e32 v252, s98
	v_mov_b32_e32 v251, 1
	global_atomic_add v252, v251, s[10:11]
.Lp4_c2done:
	s_mov_b64 exec, s[100:101]
	s_mov_b32 s0, 0x20000
	v_lshl_add_u32 v10, s91, 9, v0
	v_cmp_gt_i32_e32 vcc, s0, v10
	s_and_saveexec_b64 s[0:1], vcc
	s_cbranch_execz .LBB0_403
	s_lshl_b32 s14, s91, 9
	s_lshl_b32 s5, s6, 9
	v_add_u16_e32 v11, s14, v0
	s_mov_b64 s[50:51], 0
	s_mov_b64 s[18:19], 0x80000
